# P11 epilogue: first-half conv weights loaded at the tile start, early vmcnt(0) waits removed, vmcnt(6) before second-half use
# speedup vs baseline: 1.0134x; 1.0023x over previous
; #define PG8_WAIT_V(n) asm volatile("s_waitcnt vmcnt(" #n ")" ::: "memory")
; #define PG8_BAR __builtin_amdgcn_s_barrier()
; template <class Epi>
; DI void gemm_phase(PG8_LAS unsigned char* lds, const Gemm g, const StaticOrder& S, const Epi& E) {
;     ...
;     for (;;) {
;         const bool has_next = S.next(ui + 1, nxt);
;         const char* nA = has_next ? (const char*)g.A + (size_t)nxt.pm * tstepA + (size_t)nxt.pn * g.a_pn_off : cA; const char* nB = has_next ? (const char*)g.Bt + (size_t)nxt.pn * tstepB : cB;
;         for (int t = 0; t < nt; t += 2) {
;             const bool last = (t == nt - 2);
;             const char* a1 = cA + (size_t)(t + 1) * kstep;
;             const char* a2 = last ? nA : cA + (size_t)(t + 2) * kstep; const char* b2 = last ? nB : cB + (size_t)(t + 2) * kstep;
;             const char* a3 = a2 + kstep; const char* b3 = b2 + kstep;
;             PG8_LDB(B0, 0, 0); PG8_LDB(B1, 0, 1); PG8_SCHED; PG8_LDA(At, 0, 0); PG8_STAGE(PG8_SA(1, 1), a1 + hstepA, voffA);
;             PG8_WAIT_V(8); PG8_WAIT_L(0); PG8_BAR; PG8_MMA(0, 0, At, B0); PG8_MMA(0, 1, At, B1); PG8_BAR; PG8_SCHED;
;             PG8_LDA(At, 0, 1); PG8_STAGE(PG8_SB(0, 0), b2, voffB); PG8_STAGE(PG8_SB(0, 1), b2 + hstepB, voffB); PG8_STAGE(PG8_SA(0, 0), a2, voffA);
;             PG8_WAIT_V(8); PG8_WAIT_L(0); PG8_BAR; PG8_MMA(1, 0, At, B0); PG8_MMA(1, 1, At, B1); PG8_BAR; PG8_SCHED;
;             PG8_LDB(B0, 1, 0); PG8_LDB(B1, 1, 1); PG8_SCHED; PG8_LDA(At, 1, 0); PG8_STAGE(PG8_SA(0, 1), a2 + hstepA, voffA);
;             PG8_WAIT_V(8); PG8_WAIT_L(0); PG8_BAR; PG8_MMA(0, 0, At, B0); PG8_MMA(0, 1, At, B1); PG8_BAR; PG8_SCHED;
;             PG8_LDA(At, 1, 1); PG8_STAGE(PG8_SB(1, 0), b3, voffB); PG8_STAGE(PG8_SB(1, 1), b3 + hstepB, voffB); PG8_STAGE(PG8_SA(1, 0), a3, voffA);
;             PG8_WAIT_V(8); PG8_WAIT_L(0); PG8_BAR; PG8_MMA(1, 0, At, B0); PG8_MMA(1, 1, At, B1); PG8_BAR; PG8_SCHED;
;         }
;         if (wr == 0) PG8_BAR;
;         { int efr = fr, efq = fq; asm volatile("" : "+v"(efr), "+v"(efq)); E(acc, cur, wr, wc, efr, efq); }
;         if (!has_next) break;
; #pragma unroll
;         for (int a = 0; a < 2; ++a)
; #pragma unroll
;             for (int b = 0; b < 2; ++b)
; #pragma unroll
;                 for (int m = 0; m < 4; ++m)
; #pragma unroll
;                     for (int n = 0; n < 2; ++n) acc[a][b][m][n] = (f32x4){0.f, 0.f, 0.f, 0.f};
.LBB0_1060:
	s_lshl_b32 s84, s6, 8
	s_or_b32 s84, s84, s49
	v_lshl_add_u32 v251, v197, 3, s84
	v_ashrrev_i32_e32 v251, 1, v251
	v_lshlrev_b32_e32 v251, 2, v251
	global_load_dwordx4 v[236:239], v251, s[58:59]
	global_load_dwordx4 v[240:243], v251, s[22:23]
	global_load_dwordx4 v[244:247], v251, s[24:25]
	global_load_dwordx2 v[248:249], v251, s[60:61]
	global_load_dwordx2 v[252:253], v251, s[60:61] offset:8
	s_ashr_i32 s29, s28, 31
	s_lshl_b64 s[30:31], s[28:29], 19
	s_add_u32 s30, s96, s30
	s_addc_u32 s31, s97, s31
	s_and_b64 s[34:35], s[8:9], exec
	s_cselect_b32 s5, s31, s37
	s_cselect_b32 s7, s30, s36
	s_ashr_i32 s27, s26, 31
	s_lshl_b64 s[34:35], s[26:27], 19
	s_add_u32 s34, s3, s34
	s_addc_u32 s35, s42, s35
	s_and_b64 s[40:41], s[8:9], exec
	s_cselect_b32 s27, s35, s39
	s_cselect_b32 s29, s34, s38
	s_add_u32 s36, s36, 0x40080
	s_addc_u32 s37, s37, 0
	s_add_u32 s78, s38, 0x100
	v_mov_b32_e32 v0, 0
	s_addc_u32 s79, s39, 0
	s_mov_b32 s80, -2
	v_mov_b32_e32 v1, v0
	v_mov_b32_e32 v2, v0
	v_mov_b32_e32 v3, v0
	v_mov_b32_e32 v4, v0
	v_mov_b32_e32 v5, v0
	v_mov_b32_e32 v6, v0
	v_mov_b32_e32 v7, v0
	v_mov_b32_e32 v8, v0
	v_mov_b32_e32 v9, v0
	v_mov_b32_e32 v10, v0
	v_mov_b32_e32 v11, v0
	v_mov_b32_e32 v12, v0
	v_mov_b32_e32 v13, v0
	v_mov_b32_e32 v14, v0
	v_mov_b32_e32 v15, v0
	v_mov_b32_e32 v16, v0
	v_mov_b32_e32 v17, v0
	v_mov_b32_e32 v18, v0
	v_mov_b32_e32 v19, v0
	v_mov_b32_e32 v20, v0
	v_mov_b32_e32 v21, v0
	v_mov_b32_e32 v22, v0
	v_mov_b32_e32 v23, v0
	v_mov_b32_e32 v24, v0
	v_mov_b32_e32 v25, v0
	v_mov_b32_e32 v26, v0
	v_mov_b32_e32 v27, v0
	v_mov_b32_e32 v28, v0
	v_mov_b32_e32 v29, v0
	v_mov_b32_e32 v30, v0
	v_mov_b32_e32 v31, v0
	v_mov_b32_e32 v80, v0
	v_mov_b32_e32 v81, v0
	v_mov_b32_e32 v82, v0
	v_mov_b32_e32 v83, v0
	v_mov_b32_e32 v84, v0
	v_mov_b32_e32 v85, v0
	v_mov_b32_e32 v86, v0
	v_mov_b32_e32 v87, v0
	v_mov_b32_e32 v88, v0
	v_mov_b32_e32 v89, v0
	v_mov_b32_e32 v90, v0
	v_mov_b32_e32 v91, v0
	v_mov_b32_e32 v92, v0
	v_mov_b32_e32 v93, v0
	v_mov_b32_e32 v94, v0
	v_mov_b32_e32 v95, v0
	v_mov_b32_e32 v96, v0
	v_mov_b32_e32 v97, v0
	v_mov_b32_e32 v98, v0
	v_mov_b32_e32 v99, v0
	v_mov_b32_e32 v100, v0
	v_mov_b32_e32 v101, v0
	v_mov_b32_e32 v102, v0
	v_mov_b32_e32 v103, v0
	v_mov_b32_e32 v104, v0
	v_mov_b32_e32 v105, v0
	v_mov_b32_e32 v106, v0
	v_mov_b32_e32 v107, v0
	v_mov_b32_e32 v108, v0
	v_mov_b32_e32 v109, v0
	v_mov_b32_e32 v110, v0
	v_mov_b32_e32 v111, v0
	v_mov_b32_e32 v32, v0
	v_mov_b32_e32 v33, v0
	v_mov_b32_e32 v34, v0
	v_mov_b32_e32 v35, v0
	v_mov_b32_e32 v36, v0
	v_mov_b32_e32 v37, v0
	v_mov_b32_e32 v38, v0
	v_mov_b32_e32 v39, v0
	v_mov_b32_e32 v40, v0
	v_mov_b32_e32 v41, v0
	v_mov_b32_e32 v42, v0
	v_mov_b32_e32 v43, v0
	v_mov_b32_e32 v44, v0
	v_mov_b32_e32 v45, v0
	v_mov_b32_e32 v46, v0
	v_mov_b32_e32 v47, v0
	v_mov_b32_e32 v48, v0
	v_mov_b32_e32 v49, v0
	v_mov_b32_e32 v50, v0
	v_mov_b32_e32 v51, v0
	v_mov_b32_e32 v52, v0
	v_mov_b32_e32 v53, v0
	v_mov_b32_e32 v54, v0
	v_mov_b32_e32 v55, v0
	v_mov_b32_e32 v56, v0
	v_mov_b32_e32 v57, v0
	v_mov_b32_e32 v58, v0
	v_mov_b32_e32 v59, v0
	v_mov_b32_e32 v60, v0
	v_mov_b32_e32 v61, v0
	v_mov_b32_e32 v62, v0
	v_mov_b32_e32 v63, v0
	v_mov_b32_e32 v112, v0
	v_mov_b32_e32 v113, v0
	v_mov_b32_e32 v114, v0
	v_mov_b32_e32 v115, v0
	v_mov_b32_e32 v116, v0
	v_mov_b32_e32 v117, v0
	v_mov_b32_e32 v118, v0
	v_mov_b32_e32 v119, v0
	v_mov_b32_e32 v120, v0
	v_mov_b32_e32 v121, v0
	v_mov_b32_e32 v122, v0
	v_mov_b32_e32 v123, v0
	v_mov_b32_e32 v124, v0
	v_mov_b32_e32 v125, v0
	v_mov_b32_e32 v126, v0
	v_mov_b32_e32 v127, v0
	v_mov_b32_e32 v128, v0
	v_mov_b32_e32 v129, v0
	v_mov_b32_e32 v130, v0
	v_mov_b32_e32 v131, v0
	v_mov_b32_e32 v132, v0
	v_mov_b32_e32 v133, v0
	v_mov_b32_e32 v134, v0
	v_mov_b32_e32 v135, v0
	v_mov_b32_e32 v136, v0
	v_mov_b32_e32 v137, v0
	v_mov_b32_e32 v138, v0
	v_mov_b32_e32 v139, v0
	v_mov_b32_e32 v152, v0
	v_mov_b32_e32 v153, v0
	v_mov_b32_e32 v154, v0
	v_mov_b32_e32 v155, v0

;     DI void operator()(const f32x4 (&acc)[2][2][4][2], const pg8::Unit& u, int wr, int wc, int fr, int fq) const {
;         const int lane = fq * 16 + fr;
;         const int src1 = (lane & 48) | ((fr + 15) & 15), src2 = (lane & 48) | ((fr + 14) & 15);
;         float4 w0v[2], w1v[2], w2v[2], bbv[2];
; #pragma unroll
;         for (int bj = 0; bj < 2; ++bj) {
;             const int hc = (u.pn * 256 + bj * 128 + wc * 32 + 8 * fq) >> 1;
;             w0v[bj] = *(const float4*)(cw + hc); w1v[bj] = *(const float4*)(cw + FH + hc); w2v[bj] = *(const float4*)(cw + 2 * FH + hc); bbv[bj] = *(const float4*)(cb + hc);
;         }
; #pragma unroll
;         for (int bj = 0; bj < 2; ++bj) {
;             const int hc = (u.pn * 256 + bj * 128 + wc * 32 + 8 * fq) >> 1;
;             const float4 w0 = w0v[bj], w1 = w1v[bj], w2 = w2v[bj], bb = bbv[bj];
; #pragma unroll
;             for (int ai = 0; ai < 2; ++ai) {
;                 f32x4 gprev = (f32x4){0.f, 0.f, 0.f, 0.f};
; #pragma unroll
;                 for (int m = 0; m < 4; ++m) {
;                     const f32x4 v = acc[ai][bj][m][0], g = acc[ai][bj][m][1];
;                     f32x4 p1, p2;
; #pragma unroll
;                     for (int r = 0; r < 4; ++r) {
;                         p1[r] = __builtin_bit_cast(float, __builtin_amdgcn_update_dpp(0, __builtin_bit_cast(int, (fr == 15) ? gprev[r] : g[r]), 0x121, 0xF, 0xF, false));
;                         p2[r] = __builtin_bit_cast(float, __builtin_amdgcn_update_dpp(0, __builtin_bit_cast(int, (fr >= 14) ? gprev[r] : g[r]), 0x122, 0xF, 0xF, false));
;                     }
;                     const int row = u.pm * 256 + ai * 128 + wr * 64 + m * 16 + fr;
;                     const int wb = row >> 6;
;                     if (m == 0 && fr < 2) {
;                         *(f32x4*)(gfirst + ((size_t)wb * 2 + fr) * FH + hc) = g;
;                         *(f32x4*)(vfirst + ((size_t)wb * 2 + fr) * FH + hc) = v;
;                     } else {
;                         f32x4 o;
;                         o[0] = gelu_t(bb.x + w0.x * p2[0] + w1.x * p1[0] + w2.x * g[0]) * v[0];
;                         o[1] = gelu_t(bb.y + w0.y * p2[1] + w1.y * p1[1] + w2.y * g[1]) * v[1];
;                         o[2] = gelu_t(bb.z + w0.z * p2[2] + w1.z * p1[2] + w2.z * g[2]) * v[2];
;                         o[3] = gelu_t(bb.w + w0.w * p2[3] + w1.w * p1[3] + w2.w * g[3]) * v[3];
.LBB0_1064:
	v_mov_b32_e32 v230, 0xbdd2d3e7
	v_mov_b32_e32 v231, 0xbdd2d3e7
	v_mov_b32_e32 v232, 0xc0135761
	v_mov_b32_e32 v233, 0xc0135761
	v_mov_b32_e32 v234, 1.0
	v_mov_b32_e32 v235, 1.0
	s_lshl_b32 s5, s6, 8
	v_mov_b32_e32 v180, v196
	v_mov_b32_e32 v64, v197
	s_or_b32 s5, s5, s49
	s_lshl_b32 s4, s4, 8
	v_lshl_add_u32 v72, v64, 3, s5
	v_ashrrev_i32_e32 v184, 1, v72
	v_ashrrev_i32_e32 v185, 31, v184
	v_lshlrev_b64 v[188:189], 2, v[184:185]
	v_lshl_add_u64 v[64:65], s[58:59], 0, v[188:189]
	v_lshl_add_u64 v[66:67], s[22:23], 0, v[188:189]
	v_lshl_add_u64 v[68:69], s[24:25], 0, v[188:189]
	v_lshl_add_u64 v[70:71], s[60:61], 0, v[188:189]
	v_mov_b64_e32 v[140:141], v[236:237]
	v_mov_b64_e32 v[142:143], v[238:239]
	v_mov_b64_e32 v[144:145], v[240:241]
	v_mov_b64_e32 v[146:147], v[242:243]
	v_mov_b64_e32 v[148:149], v[244:245]
	v_mov_b64_e32 v[150:151], v[246:247]
	v_mov_b64_e32 v[156:157], v[248:249]
	v_mov_b64_e32 v[158:159], v[252:253]
	v_add_u32_e32 v64, 0x80, v72
	v_ashrrev_i32_e32 v178, 1, v64
	v_ashrrev_i32_e32 v179, 31, v178
	v_lshlrev_b64 v[182:183], 2, v[178:179]
	v_lshl_add_u64 v[64:65], s[58:59], 0, v[182:183]
	v_lshl_add_u64 v[66:67], s[22:23], 0, v[182:183]
	v_lshl_add_u64 v[76:77], s[24:25], 0, v[182:183]
	v_lshl_add_u64 v[78:79], s[60:61], 0, v[182:183]
	global_load_dwordx4 v[68:71], v[64:65], off
	global_load_dwordx4 v[72:75], v[66:67], off
	s_nop 0
	global_load_dwordx4 v[64:67], v[76:77], off
	s_nop 0
	global_load_dwordx4 v[76:79], v[78:79], off
	s_add_i32 s4, s4, s48
	v_add_u32_e32 v202, s4, v180
	v_cmp_eq_u32_e64 s[4:5], 15, v180
	v_mov_b32_e32 v192, 0
	v_cmp_lt_i32_e32 vcc, 13, v180
	v_cndmask_b32_e64 v168, v136, 0, s[4:5]
	v_mov_b32_e32 v194, 0
	v_mov_b32_e32 v193, 0
	v_mov_b32_dpp v192, v168 row_ror:1 row_mask:0xf bank_mask:0xf
	v_cndmask_b32_e64 v168, v136, 0, vcc
	v_mov_b32_e32 v195, 0
	v_mov_b32_e32 v186, 0
	v_mov_b32_dpp v194, v168 row_ror:2 row_mask:0xf bank_mask:0xf
	v_cndmask_b32_e64 v168, v137, 0, s[4:5]
	v_mov_b32_e32 v190, 0
	v_mov_b32_e32 v187, 0
	v_mov_b32_dpp v193, v168 row_ror:1 row_mask:0xf bank_mask:0xf
	v_cndmask_b32_e64 v168, v137, 0, vcc
	v_mov_b32_e32 v191, 0
	v_cmp_lt_i32_e64 s[6:7], 1, v180
	v_mov_b32_dpp v195, v168 row_ror:2 row_mask:0xf bank_mask:0xf
	v_cndmask_b32_e64 v168, v138, 0, s[4:5]
	s_nop 1
	v_mov_b32_dpp v186, v168 row_ror:1 row_mask:0xf bank_mask:0xf
	v_cndmask_b32_e64 v168, v138, 0, vcc
	s_nop 1
	v_mov_b32_dpp v190, v168 row_ror:2 row_mask:0xf bank_mask:0xf
	v_cndmask_b32_e64 v168, v139, 0, s[4:5]
	s_nop 1
	v_mov_b32_dpp v187, v168 row_ror:1 row_mask:0xf bank_mask:0xf
	v_cndmask_b32_e64 v168, v139, 0, vcc
	s_nop 1
	v_mov_b32_dpp v191, v168 row_ror:2 row_mask:0xf bank_mask:0xf
	s_and_saveexec_b64 s[36:37], s[6:7]
	s_xor_b64 s[36:37], exec, s[36:37]
	s_cbranch_execz .LBB0_1066
	s_nop 0
	v_pk_fma_f32 v[194:195], v[140:141], v[194:195], v[156:157]
	v_pk_fma_f32 v[190:191], v[142:143], v[190:191], v[158:159]
	v_pk_fma_f32 v[192:193], v[144:145], v[192:193], v[194:195]
	v_pk_fma_f32 v[186:187], v[146:147], v[186:187], v[190:191]
	v_pk_fma_f32 v[192:193], v[136:137], v[148:149], v[192:193]
	v_pk_fma_f32 v[186:187], v[138:139], v[150:151], v[186:187]
	v_pk_mul_f32 v[228:229], v[192:193], v[192:193]
	v_pk_fma_f32 v[228:229], v[228:229], v[230:231], v[232:233]
	v_pk_mul_f32 v[228:229], v[228:229], v[192:193]
	v_exp_f32_e32 v228, v228
	v_exp_f32_e32 v229, v229
	s_nop 0
	v_pk_add_f32 v[228:229], v[228:229], v[234:235]
	v_rcp_f32_e32 v194, v228
	v_rcp_f32_e32 v195, v229
	s_nop 0
	v_pk_mul_f32 v[192:193], v[192:193], v[194:195]
	v_pk_mul_f32 v[228:229], v[186:187], v[186:187]
	v_pk_fma_f32 v[228:229], v[228:229], v[230:231], v[232:233]
	v_pk_mul_f32 v[228:229], v[228:229], v[186:187]
	v_exp_f32_e32 v228, v228
	v_exp_f32_e32 v229, v229
	s_nop 0
	v_pk_add_f32 v[228:229], v[228:229], v[234:235]
	v_rcp_f32_e32 v190, v228
	v_rcp_f32_e32 v191, v229
	s_nop 0
	v_pk_mul_f32 v[186:187], v[186:187], v[190:191]
	s_nop 0
	v_pk_mul_f32 v[186:187], v[154:155], v[186:187]
	v_pk_mul_f32 v[192:193], v[152:153], v[192:193]
	v_cvt_pk_bf16_f32 v191, v186, v187
	v_mov_b64_e32 v[186:187], s[72:73]
	v_mad_i64_i32 v[186:187], s[38:39], v202, s76, v[186:187]
	v_cvt_pk_bf16_f32 v190, v192, v193
	v_lshl_add_u64 v[186:187], v[184:185], 1, v[186:187]
	global_store_dwordx2 v[186:187], v[190:191], off

; DI uint2 pk4(f32x4 v) { return make_uint2(pk2(v[0], v[1]), pk2(v[2], v[3])); }
; DI float gelu_t(float x) { float u = 1.5957691216057308f * (x + 0.044715f * x * x * x); return x * __builtin_amdgcn_rcpf(1.f + __expf(-u)); }
;     DI void operator()(const f32x4 (&acc)[2][2][4][2], const pg8::Unit& u, int wr, int wc, int fr, int fq) const {
;     ...
;         for (int bj = 0; bj < 2; ++bj) {
;             const int hc = (u.pn * 256 + bj * 128 + wc * 32 + 8 * fq) >> 1;
;             const float4 w0 = w0v[bj], w1 = w1v[bj], w2 = w2v[bj], bb = bbv[bj];
; #pragma unroll
;             for (int ai = 0; ai < 2; ++ai) {
;                 f32x4 gprev = (f32x4){0.f, 0.f, 0.f, 0.f};
; #pragma unroll
;                 for (int m = 0; m < 4; ++m) {
;                     const f32x4 v = acc[ai][bj][m][0], g = acc[ai][bj][m][1];
;                     f32x4 p1, p2;
; #pragma unroll
;                     for (int r = 0; r < 4; ++r) {
;                         p1[r] = __builtin_bit_cast(float, __builtin_amdgcn_update_dpp(0, __builtin_bit_cast(int, (fr == 15) ? gprev[r] : g[r]), 0x121, 0xF, 0xF, false));
;                         p2[r] = __builtin_bit_cast(float, __builtin_amdgcn_update_dpp(0, __builtin_bit_cast(int, (fr >= 14) ? gprev[r] : g[r]), 0x122, 0xF, 0xF, false));
;                     }
;                     const int row = u.pm * 256 + ai * 128 + wr * 64 + m * 16 + fr;
;                     const int wb = row >> 6;
;                     if (m == 0 && fr < 2) {
;                         *(f32x4*)(gfirst + ((size_t)wb * 2 + fr) * FH + hc) = g;
;                         *(f32x4*)(vfirst + ((size_t)wb * 2 + fr) * FH + hc) = v;
;                     } else {
;                         f32x4 o;
;                         o[0] = gelu_t(bb.x + w0.x * p2[0] + w1.x * p1[0] + w2.x * g[0]) * v[0];
;                         o[1] = gelu_t(bb.y + w0.y * p2[1] + w1.y * p1[1] + w2.y * g[1]) * v[1];
;                         o[2] = gelu_t(bb.z + w0.z * p2[2] + w1.z * p1[2] + w2.z * g[2]) * v[2];
;                         o[3] = gelu_t(bb.w + w0.w * p2[3] + w1.w * p1[3] + w2.w * g[3]) * v[3];
;                         *(uint2*)(hid + (size_t)row * FH + hc) = pk4(o);
;                     }
;                     if (m == 3 && fr >= 14) *(f32x4*)(glast + ((size_t)wb * 2 + (fr - 14)) * FH + hc) = g;
;                     gprev = g;
;                 }
.LBB0_1068:
	s_or_b64 exec, exec, s[36:37]
	s_nop 0
	v_cndmask_b32_e64 v153, v128, v136, s[4:5]
	v_cndmask_b32_e64 v154, v129, v137, s[4:5]
	v_cndmask_b32_e64 v155, v130, v138, s[4:5]
	v_mov_b32_dpp v152, v153 row_ror:1 row_mask:0xf bank_mask:0xf
	v_cndmask_b32_e32 v153, v128, v136, vcc
	v_cndmask_b32_e64 v190, v131, v139, s[4:5]
	v_add_u32_e32 v168, -14, v180
	v_mov_b32_dpp v136, v153 row_ror:2 row_mask:0xf bank_mask:0xf
	s_nop 1
	v_mov_b32_dpp v153, v154 row_ror:1 row_mask:0xf bank_mask:0xf
	v_cndmask_b32_e32 v154, v129, v137, vcc
	s_nop 1
	v_mov_b32_dpp v137, v154 row_ror:2 row_mask:0xf bank_mask:0xf
	s_nop 0
	v_pk_fma_f32 v[136:137], v[140:141], v[136:137], v[156:157]
	v_mov_b32_dpp v154, v155 row_ror:1 row_mask:0xf bank_mask:0xf
	v_cndmask_b32_e32 v155, v130, v138, vcc
	v_pk_fma_f32 v[136:137], v[144:145], v[152:153], v[136:137]
	s_nop 0
	v_mov_b32_dpp v138, v155 row_ror:2 row_mask:0xf bank_mask:0xf
	v_pk_fma_f32 v[136:137], v[128:129], v[148:149], v[136:137]
	s_nop 0
	v_mov_b32_dpp v155, v190 row_ror:1 row_mask:0xf bank_mask:0xf
	v_cndmask_b32_e32 v190, v131, v139, vcc
	s_nop 1
	v_mov_b32_dpp v139, v190 row_ror:2 row_mask:0xf bank_mask:0xf
	v_pk_fma_f32 v[138:139], v[142:143], v[138:139], v[158:159]
	v_pk_fma_f32 v[138:139], v[146:147], v[154:155], v[138:139]
	v_pk_fma_f32 v[138:139], v[130:131], v[150:151], v[138:139]
	v_pk_mul_f32 v[228:229], v[136:137], v[136:137]
	v_pk_fma_f32 v[228:229], v[228:229], v[230:231], v[232:233]
	v_pk_mul_f32 v[228:229], v[228:229], v[136:137]
	v_exp_f32_e32 v228, v228
	v_exp_f32_e32 v229, v229
	s_nop 0
	v_pk_add_f32 v[228:229], v[228:229], v[234:235]
	v_rcp_f32_e32 v152, v228
	v_rcp_f32_e32 v153, v229
	s_nop 0
	v_pk_mul_f32 v[136:137], v[136:137], v[152:153]
	v_add_u32_e32 v190, 16, v202
	v_pk_mul_f32 v[132:133], v[132:133], v[136:137]
	v_pk_mul_f32 v[228:229], v[138:139], v[138:139]
	v_pk_fma_f32 v[228:229], v[228:229], v[230:231], v[232:233]
	v_pk_mul_f32 v[228:229], v[228:229], v[138:139]
	v_exp_f32_e32 v228, v228
	v_exp_f32_e32 v229, v229
	s_nop 0
	v_pk_add_f32 v[228:229], v[228:229], v[234:235]
	v_rcp_f32_e32 v154, v228
	v_rcp_f32_e32 v155, v229
	s_nop 0
	v_pk_mul_f32 v[136:137], v[138:139], v[154:155]
	v_mov_b64_e32 v[138:139], s[72:73]
	v_pk_mul_f32 v[134:135], v[134:135], v[136:137]
	v_cvt_pk_bf16_f32 v136, v132, v133
	v_cvt_pk_bf16_f32 v137, v134, v135
	v_mad_i64_i32 v[132:133], s[36:37], v190, s76, v[138:139]
	v_lshlrev_b64 v[134:135], 1, v[184:185]
	v_lshl_add_u64 v[152:153], v[132:133], 0, v[134:135]
	global_store_dwordx2 v[152:153], v[136:137], off
	v_cndmask_b32_e64 v137, v120, v128, s[4:5]
	v_cndmask_b32_e64 v152, v121, v129, s[4:5]
	v_cndmask_b32_e64 v153, v122, v130, s[4:5]
	v_mov_b32_dpp v136, v137 row_ror:1 row_mask:0xf bank_mask:0xf
	v_cndmask_b32_e32 v137, v120, v128, vcc
	v_cndmask_b32_e64 v154, v123, v131, s[4:5]
	s_nop 0
	v_mov_b32_dpp v128, v137 row_ror:2 row_mask:0xf bank_mask:0xf
	s_nop 1
	v_mov_b32_dpp v137, v152 row_ror:1 row_mask:0xf bank_mask:0xf
	v_cndmask_b32_e32 v152, v121, v129, vcc
	s_nop 1
	v_mov_b32_dpp v129, v152 row_ror:2 row_mask:0xf bank_mask:0xf
	v_pk_fma_f32 v[128:129], v[140:141], v[128:129], v[156:157]
	s_nop 0
	v_mov_b32_dpp v152, v153 row_ror:1 row_mask:0xf bank_mask:0xf
	v_cndmask_b32_e32 v153, v122, v130, vcc
	v_pk_fma_f32 v[128:129], v[144:145], v[136:137], v[128:129]
	s_nop 0
	v_mov_b32_dpp v130, v153 row_ror:2 row_mask:0xf bank_mask:0xf
	v_pk_fma_f32 v[128:129], v[120:121], v[148:149], v[128:129]
	s_nop 0
	v_mov_b32_dpp v153, v154 row_ror:1 row_mask:0xf bank_mask:0xf
	v_cndmask_b32_e32 v154, v123, v131, vcc
	s_nop 1
	v_mov_b32_dpp v131, v154 row_ror:2 row_mask:0xf bank_mask:0xf
	v_pk_fma_f32 v[130:131], v[142:143], v[130:131], v[158:159]
	v_pk_fma_f32 v[130:131], v[146:147], v[152:153], v[130:131]
	v_pk_fma_f32 v[130:131], v[122:123], v[150:151], v[130:131]
	v_pk_mul_f32 v[228:229], v[128:129], v[128:129]
; DI uint2 pk4(f32x4 v) { return make_uint2(pk2(v[0], v[1]), pk2(v[2], v[3])); }
; DI float gelu_t(float x) { float u = 1.5957691216057308f * (x + 0.044715f * x * x * x); return x * __builtin_amdgcn_rcpf(1.f + __expf(-u)); }
;     DI void operator()(const f32x4 (&acc)[2][2][4][2], const pg8::Unit& u, int wr, int wc, int fr, int fq) const {
;     ...
;                 for (int m = 0; m < 4; ++m) {
;                     const f32x4 v = acc[ai][bj][m][0], g = acc[ai][bj][m][1];
;                     f32x4 p1, p2;
; #pragma unroll
;                     for (int r = 0; r < 4; ++r) {
;                         p1[r] = __builtin_bit_cast(float, __builtin_amdgcn_update_dpp(0, __builtin_bit_cast(int, (fr == 15) ? gprev[r] : g[r]), 0x121, 0xF, 0xF, false));
;                         p2[r] = __builtin_bit_cast(float, __builtin_amdgcn_update_dpp(0, __builtin_bit_cast(int, (fr >= 14) ? gprev[r] : g[r]), 0x122, 0xF, 0xF, false));
;                     }
;                     const int row = u.pm * 256 + ai * 128 + wr * 64 + m * 16 + fr;
;                     const int wb = row >> 6;
;                     if (m == 0 && fr < 2) {
;                         *(f32x4*)(gfirst + ((size_t)wb * 2 + fr) * FH + hc) = g;
;                         *(f32x4*)(vfirst + ((size_t)wb * 2 + fr) * FH + hc) = v;
;                     } else {
;                         f32x4 o;
;                         o[0] = gelu_t(bb.x + w0.x * p2[0] + w1.x * p1[0] + w2.x * g[0]) * v[0];
;                         o[1] = gelu_t(bb.y + w0.y * p2[1] + w1.y * p1[1] + w2.y * g[1]) * v[1];
;                         o[2] = gelu_t(bb.z + w0.z * p2[2] + w1.z * p1[2] + w2.z * g[2]) * v[2];
;                         o[3] = gelu_t(bb.w + w0.w * p2[3] + w1.w * p1[3] + w2.w * g[3]) * v[3];
;                         *(uint2*)(hid + (size_t)row * FH + hc) = pk4(o);
;                     }
;                     if (m == 3 && fr >= 14) *(f32x4*)(glast + ((size_t)wb * 2 + (fr - 14)) * FH + hc) = g;
;                     gprev = g;
;                 }
	v_pk_fma_f32 v[228:229], v[228:229], v[230:231], v[232:233]
	v_pk_mul_f32 v[228:229], v[228:229], v[128:129]
	v_exp_f32_e32 v228, v228
	v_exp_f32_e32 v229, v229
	s_nop 0
	v_pk_add_f32 v[228:229], v[228:229], v[234:235]
	v_rcp_f32_e32 v136, v228
	v_rcp_f32_e32 v137, v229
	s_nop 0
	v_pk_mul_f32 v[128:129], v[128:129], v[136:137]
	v_add_u32_e32 v154, 32, v202
	v_pk_mul_f32 v[124:125], v[124:125], v[128:129]
	v_pk_mul_f32 v[228:229], v[130:131], v[130:131]
	v_pk_fma_f32 v[228:229], v[228:229], v[230:231], v[232:233]
	v_pk_mul_f32 v[228:229], v[228:229], v[130:131]
	v_exp_f32_e32 v228, v228
	v_exp_f32_e32 v229, v229
	s_nop 0
	v_pk_add_f32 v[228:229], v[228:229], v[234:235]
	v_rcp_f32_e32 v152, v228
	v_rcp_f32_e32 v153, v229
	s_nop 0
	v_pk_mul_f32 v[128:129], v[130:131], v[152:153]
	v_cndmask_b32_e64 v130, v115, v123, s[4:5]
	v_pk_mul_f32 v[126:127], v[126:127], v[128:129]
	v_cvt_pk_bf16_f32 v128, v124, v125
	v_mad_i64_i32 v[124:125], s[36:37], v154, s76, v[138:139]
	v_cvt_pk_bf16_f32 v129, v126, v127
	v_lshl_add_u64 v[126:127], v[124:125], 0, v[134:135]
	global_store_dwordx2 v[126:127], v[128:129], off
	v_cndmask_b32_e64 v127, v112, v120, s[4:5]
	v_cndmask_b32_e64 v128, v113, v121, s[4:5]
	v_cndmask_b32_e64 v129, v114, v122, s[4:5]
	v_mov_b32_dpp v126, v127 row_ror:1 row_mask:0xf bank_mask:0xf
	v_cndmask_b32_e32 v127, v112, v120, vcc
	v_add_u32_e32 v136, 48, v202
	s_nop 0
	v_mov_b32_dpp v120, v127 row_ror:2 row_mask:0xf bank_mask:0xf
	s_nop 1
	v_mov_b32_dpp v127, v128 row_ror:1 row_mask:0xf bank_mask:0xf
	v_cndmask_b32_e32 v128, v113, v121, vcc
	s_nop 1
	v_mov_b32_dpp v121, v128 row_ror:2 row_mask:0xf bank_mask:0xf
	v_pk_fma_f32 v[120:121], v[140:141], v[120:121], v[156:157]
	v_pk_fma_f32 v[120:121], v[144:145], v[126:127], v[120:121]
	s_nop 0
	v_pk_fma_f32 v[126:127], v[112:113], v[148:149], v[120:121]
	v_mov_b32_dpp v128, v129 row_ror:1 row_mask:0xf bank_mask:0xf
	v_cndmask_b32_e32 v129, v114, v122, vcc
	s_nop 1
	v_mov_b32_dpp v122, v129 row_ror:2 row_mask:0xf bank_mask:0xf
	v_mov_b32_dpp v129, v130 row_ror:1 row_mask:0xf bank_mask:0xf
	v_cndmask_b32_e32 v130, v115, v123, vcc
	s_nop 1
	v_mov_b32_dpp v123, v130 row_ror:2 row_mask:0xf bank_mask:0xf
	v_pk_fma_f32 v[120:121], v[142:143], v[122:123], v[158:159]
	v_pk_mul_f32 v[228:229], v[126:127], v[126:127]
	v_pk_fma_f32 v[228:229], v[228:229], v[230:231], v[232:233]
	v_pk_mul_f32 v[228:229], v[228:229], v[126:127]
	v_exp_f32_e32 v228, v228
	v_exp_f32_e32 v229, v229
	s_nop 0
	v_pk_add_f32 v[228:229], v[228:229], v[234:235]
	v_rcp_f32_e32 v130, v228
	v_rcp_f32_e32 v131, v229
	s_nop 0
	v_pk_mul_f32 v[126:127], v[126:127], v[130:131]
	v_pk_fma_f32 v[120:121], v[146:147], v[128:129], v[120:121]
	v_pk_mul_f32 v[116:117], v[116:117], v[126:127]
	v_pk_fma_f32 v[122:123], v[114:115], v[150:151], v[120:121]
	s_nop 0
	v_ashrrev_i32_e32 v120, 6, v136
	v_ashrrev_i32_e32 v121, 31, v120
	v_pk_mul_f32 v[228:229], v[122:123], v[122:123]
	v_pk_fma_f32 v[228:229], v[228:229], v[230:231], v[232:233]
	v_pk_mul_f32 v[228:229], v[228:229], v[122:123]
	v_exp_f32_e32 v228, v228
	v_exp_f32_e32 v229, v229
	s_nop 0
	v_pk_add_f32 v[228:229], v[228:229], v[234:235]
	v_rcp_f32_e32 v128, v228
	v_rcp_f32_e32 v129, v229
	s_nop 0
	v_pk_mul_f32 v[122:123], v[122:123], v[128:129]
	s_nop 0
	v_pk_mul_f32 v[118:119], v[118:119], v[122:123]
	v_cvt_pk_bf16_f32 v122, v116, v117
	v_mad_i64_i32 v[116:117], s[36:37], v136, s76, v[138:139]
	v_cvt_pk_bf16_f32 v123, v118, v119
	v_lshl_add_u64 v[118:119], v[116:117], 0, v[134:135]
	global_store_dwordx2 v[118:119], v[122:123], off
	s_and_saveexec_b64 s[36:37], vcc
	s_cbranch_execz .LBB0_1070
	v_lshl_add_u64 v[118:119], v[120:121], 1, v[168:169]
	v_mov_b64_e32 v[122:123], s[68:69]
	v_mad_u64_u32 v[122:123], s[38:39], v118, s77, v[122:123]
	v_mad_i32_i24 v123, v119, s77, v123
	v_lshl_add_u64 v[118:119], v[184:185], 2, v[122:123]
	global_store_dwordx4 v[118:119], v[112:115], off

;     DI void operator()(const f32x4 (&acc)[2][2][4][2], const pg8::Unit& u, int wr, int wc, int fr, int fq) const {
;     ...
;         float4 w0v[2], w1v[2], w2v[2], bbv[2];
; #pragma unroll
;         for (int bj = 0; bj < 2; ++bj) {
;             const int hc = (u.pn * 256 + bj * 128 + wc * 32 + 8 * fq) >> 1;
;             w0v[bj] = *(const float4*)(cw + hc); w1v[bj] = *(const float4*)(cw + FH + hc); w2v[bj] = *(const float4*)(cw + 2 * FH + hc); bbv[bj] = *(const float4*)(cb + hc);
;         }
; #pragma unroll
;         for (int bj = 0; bj < 2; ++bj) {
;             const int hc = (u.pn * 256 + bj * 128 + wc * 32 + 8 * fq) >> 1;
;             const float4 w0 = w0v[bj], w1 = w1v[bj], w2 = w2v[bj], bb = bbv[bj];
; #pragma unroll
;             for (int ai = 0; ai < 2; ++ai) {
;                 f32x4 gprev = (f32x4){0.f, 0.f, 0.f, 0.f};
; #pragma unroll
;                 for (int m = 0; m < 4; ++m) {
;                     const f32x4 v = acc[ai][bj][m][0], g = acc[ai][bj][m][1];
;                     f32x4 p1, p2;
; #pragma unroll
;                     for (int r = 0; r < 4; ++r) {
;                         p1[r] = __builtin_bit_cast(float, __builtin_amdgcn_update_dpp(0, __builtin_bit_cast(int, (fr == 15) ? gprev[r] : g[r]), 0x121, 0xF, 0xF, false));
;                         p2[r] = __builtin_bit_cast(float, __builtin_amdgcn_update_dpp(0, __builtin_bit_cast(int, (fr >= 14) ? gprev[r] : g[r]), 0x122, 0xF, 0xF, false));
;                     }
;                     const int row = u.pm * 256 + ai * 128 + wr * 64 + m * 16 + fr;
;                     const int wb = row >> 6;
;                     if (m == 0 && fr < 2) {
;                         *(f32x4*)(gfirst + ((size_t)wb * 2 + fr) * FH + hc) = g;
;                         *(f32x4*)(vfirst + ((size_t)wb * 2 + fr) * FH + hc) = v;
;                     } else {
;                         f32x4 o;
;                         o[0] = gelu_t(bb.x + w0.x * p2[0] + w1.x * p1[0] + w2.x * g[0]) * v[0];
;                         o[1] = gelu_t(bb.y + w0.y * p2[1] + w1.y * p1[1] + w2.y * g[1]) * v[1];
;                         o[2] = gelu_t(bb.z + w0.z * p2[2] + w1.z * p1[2] + w2.z * g[2]) * v[2];
;                         o[3] = gelu_t(bb.w + w0.w * p2[3] + w1.w * p1[3] + w2.w * g[3]) * v[3];
;                         *(uint2*)(hid + (size_t)row * FH + hc) = pk4(o);
;                     }
.LBB0_1076:
	s_or_b64 exec, exec, s[36:37]
	s_nop 0
	v_cndmask_b32_e64 v80, v56, 0, s[4:5]
	s_nop 1
	v_mov_b32_dpp v86, v80 row_ror:1 row_mask:0xf bank_mask:0xf
	v_cndmask_b32_e64 v80, v56, 0, vcc
	v_cndmask_b32_e64 v81, v58, 0, s[4:5]
	s_nop 0
	v_mov_b32_dpp v90, v80 row_ror:2 row_mask:0xf bank_mask:0xf
	v_cndmask_b32_e64 v80, v57, 0, s[4:5]
	v_cndmask_b32_e64 v83, v59, 0, s[4:5]
	s_nop 0
	v_mov_b32_dpp v87, v80 row_ror:1 row_mask:0xf bank_mask:0xf
	v_cndmask_b32_e64 v80, v57, 0, vcc
	v_cndmask_b32_e64 v94, v59, 0, vcc
	s_nop 0
	v_mov_b32_dpp v91, v80 row_ror:2 row_mask:0xf bank_mask:0xf
	s_nop 1
	v_mov_b32_dpp v80, v81 row_ror:1 row_mask:0xf bank_mask:0xf
	v_cndmask_b32_e64 v81, v58, 0, vcc
	s_nop 1
	v_mov_b32_dpp v82, v81 row_ror:2 row_mask:0xf bank_mask:0xf
	s_nop 1
	v_mov_b32_dpp v81, v83 row_ror:1 row_mask:0xf bank_mask:0xf
	s_nop 1
	v_mov_b32_dpp v83, v94 row_ror:2 row_mask:0xf bank_mask:0xf
	s_waitcnt vmcnt(6)
	s_and_saveexec_b64 s[36:37], s[6:7]
	s_xor_b64 s[36:37], exec, s[36:37]
	s_cbranch_execz .LBB0_1078
	v_pk_fma_f32 v[82:83], v[70:71], v[82:83], v[78:79]
	v_pk_fma_f32 v[90:91], v[68:69], v[90:91], v[76:77]
	v_pk_fma_f32 v[80:81], v[74:75], v[80:81], v[82:83]
	v_pk_fma_f32 v[86:87], v[72:73], v[86:87], v[90:91]
	v_pk_fma_f32 v[80:81], v[58:59], v[66:67], v[80:81]
	v_pk_fma_f32 v[86:87], v[56:57], v[64:65], v[86:87]
	v_pk_mul_f32 v[228:229], v[80:81], v[80:81]
	v_pk_fma_f32 v[228:229], v[228:229], v[230:231], v[232:233]
	v_pk_mul_f32 v[228:229], v[228:229], v[80:81]
	v_exp_f32_e32 v228, v228
	v_exp_f32_e32 v229, v229
	s_nop 0
	v_pk_add_f32 v[228:229], v[228:229], v[234:235]
	v_rcp_f32_e32 v82, v228
	v_rcp_f32_e32 v83, v229
	s_nop 0
	v_pk_mul_f32 v[80:81], v[80:81], v[82:83]
	v_pk_mul_f32 v[228:229], v[86:87], v[86:87]
	v_pk_fma_f32 v[228:229], v[228:229], v[230:231], v[232:233]
	v_pk_mul_f32 v[228:229], v[228:229], v[86:87]
	v_exp_f32_e32 v228, v228
	v_exp_f32_e32 v229, v229
	s_nop 0
	v_pk_add_f32 v[228:229], v[228:229], v[234:235]
	v_rcp_f32_e32 v90, v228
	v_rcp_f32_e32 v91, v229
	s_nop 0
	v_pk_mul_f32 v[86:87], v[86:87], v[90:91]
	v_pk_mul_f32 v[80:81], v[62:63], v[80:81]
	v_pk_mul_f32 v[86:87], v[60:61], v[86:87]
	v_cvt_pk_bf16_f32 v83, v80, v81
	v_mov_b64_e32 v[80:81], s[72:73]
	v_mad_i64_i32 v[80:81], s[38:39], v202, s76, v[80:81]
	v_cvt_pk_bf16_f32 v82, v86, v87
	v_lshl_add_u64 v[80:81], v[178:179], 1, v[80:81]
	global_store_dwordx2 v[80:81], v[82:83], off
